# attention unit epilogue: sub-norm gamma loads issued at the epilogue start into free registers instead of after the exchange barrier
# baseline (speedup 1.0000x reference)
; #define LAS __attribute__((address_space(3)))
; __device__ __forceinline__ int fresh_tid(int wave_s) { unsigned m = ~0u; asm volatile("" : "+s"(m)); int t = wave_s * 64 + (int)__builtin_amdgcn_mbcnt_hi(m, __builtin_amdgcn_mbcnt_lo(m, 0u)); asm volatile("" : "+v"(t)); return t; }
; template <bool SAMPLE> __device__ __forceinline__ void attn_unit16(const Ctx& c, LAS unsigned char* lds, int b, int h, int qb, int wave_s) {
;     ...
;     const int lane2 = fresh_tid(wave_s) & 63, c16b = lane2 & 15, q4b = lane2 >> 4;
;     LAS float* X = (LAS float*)lds;
;     if (active) {
;         float lam;
;         { const float a = c.lq1[lane2] * c.lk1[lane2], bb = c.lq2[lane2] * c.lk2[lane2]; lam = __expf(wave_sum(a)) - __expf(wave_sum(bb)) + 0.2f; }
; #pragma unroll
;         for (int qt = 0; qt < NQT; ++qt) { float l = ls[qt] + __shfl_xor(ls[qt], 16); l += __shfl_xor(l, 32);
;             const float inv = (mp ? lam : 1.f) / l;
;     ...
;         float sg[8];
; #pragma unroll
;         for (int et = 0; et < 8; ++et) sg[et] = c.subg[16 * et + c16b] * 0.8f;
.Lq1_lam_ld_done:
	v_and_b32_e32 v246, 15, v7
	v_lshlrev_b32_e32 v246, 2, v246
	global_load_dword v238, v246, s[26:27]
	global_load_dword v239, v246, s[26:27] offset:64
	global_load_dword v240, v246, s[26:27] offset:128
	global_load_dword v241, v246, s[26:27] offset:192
	global_load_dword v242, v246, s[26:27] offset:256
	global_load_dword v243, v246, s[26:27] offset:320
	global_load_dword v244, v246, s[26:27] offset:384
	global_load_dword v245, v246, s[26:27] offset:448
	v_add_u32_e32 v13, 64, v215
	v_cmp_lt_i32_e32 vcc, v5, v13
	v_xor_b32_e32 v8, 2, v212
	v_xor_b32_e32 v9, 4, v212
	v_cndmask_b32_e32 v5, v212, v5, vcc
	v_lshlrev_b32_e32 v210, 2, v5
	v_cmp_lt_i32_e32 vcc, v8, v13
	v_xor_b32_e32 v10, 8, v212
	v_xor_b32_e32 v11, 16, v212
	v_cndmask_b32_e32 v8, v212, v8, vcc
	v_lshlrev_b32_e32 v211, 2, v8
	v_cmp_lt_i32_e32 vcc, v9, v13
	v_xor_b32_e32 v12, 32, v212
	s_cmp_eq_u32 s81, 0
	v_cndmask_b32_e32 v9, v212, v9, vcc
	v_lshlrev_b32_e32 v214, 2, v9
	v_cmp_lt_i32_e32 vcc, v10, v13
	s_cselect_b64 s[2:3], -1, 0
	v_lshrrev_b32_e32 v9, 2, v7
	v_cndmask_b32_e32 v10, v212, v10, vcc
	v_cmp_lt_i32_e32 vcc, v11, v13
	v_lshlrev_b32_e32 v213, 2, v10
	s_cmp_lg_u32 s81, 0
	v_cndmask_b32_e32 v11, v212, v11, vcc
	v_cmp_lt_i32_e32 vcc, v12, v13
	v_lshlrev_b32_e32 v217, 2, v11
	ds_bpermute_b32 v8, v217, v199
	s_waitcnt lgkmcnt(0)
	v_add_f32_e32 v8, v199, v8
	s_cmp_eq_u32 s32, -1
	s_cbranch_scc0 .Lq1_lam_cached
	s_waitcnt vmcnt(2)
	v_mul_f32_e32 v5, v2, v3
	ds_bpermute_b32 v5, v210, v5
	s_waitcnt vmcnt(0)
	v_mul_f32_e32 v14, v4, v0
	ds_bpermute_b32 v14, v210, v14
	s_waitcnt lgkmcnt(1)
	v_fmac_f32_e32 v5, v2, v3
	v_cndmask_b32_e32 v3, v212, v12, vcc
	s_waitcnt lgkmcnt(0)
	v_fmac_f32_e32 v14, v4, v0
	ds_bpermute_b32 v0, v211, v5
	ds_bpermute_b32 v2, v211, v14
	v_lshlrev_b32_e32 v216, 2, v3
	ds_bpermute_b32 v12, v216, v8
	s_waitcnt lgkmcnt(2)
	v_add_f32_e32 v0, v5, v0
	s_waitcnt lgkmcnt(1)
	v_add_f32_e32 v2, v14, v2
	ds_bpermute_b32 v4, v214, v0
	ds_bpermute_b32 v5, v214, v2
	s_waitcnt lgkmcnt(1)
	v_add_f32_e32 v0, v0, v4
	s_waitcnt lgkmcnt(0)
	v_add_f32_e32 v2, v2, v5
	ds_bpermute_b32 v3, v213, v0
	ds_bpermute_b32 v4, v213, v2
	ds_bpermute_b32 v5, v217, v198
	s_waitcnt lgkmcnt(2)
	v_add_f32_e32 v0, v0, v3
	s_waitcnt lgkmcnt(1)
	v_add_f32_e32 v2, v2, v4
	ds_bpermute_b32 v3, v217, v0
	ds_bpermute_b32 v10, v217, v2
	s_waitcnt lgkmcnt(2)
	v_add_f32_e32 v5, v198, v5
	ds_bpermute_b32 v11, v216, v5
	v_and_b32_e32 v4, 12, v9
	s_waitcnt lgkmcnt(2)
	v_add_f32_e32 v0, v0, v3
	s_waitcnt lgkmcnt(1)
	v_add_f32_e32 v2, v2, v10
	ds_bpermute_b32 v3, v216, v0
	ds_bpermute_b32 v10, v216, v2
	v_or_b32_e32 v9, v215, v4
	v_lshlrev_b32_e32 v9, 2, v9
	s_waitcnt lgkmcnt(1)
	v_add_f32_e32 v0, v0, v3
	s_waitcnt lgkmcnt(0)
	v_add_f32_e32 v2, v2, v10
	v_mul_f32_e32 v0, 0x3fb8aa3b, v0
	v_mul_f32_e32 v2, 0x3fb8aa3b, v2
	v_exp_f32_e32 v0, v0
	v_exp_f32_e32 v2, v2
	v_add_f32_e32 v3, v5, v11
	v_add_f32_e32 v5, v8, v12
	v_sub_f32_e32 v0, v0, v2
	v_add_f32_e32 v0, 0x3e4ccccd, v0
	s_nop 0
	v_readfirstlane_b32 s32, v0
	s_branch .Lq1_lam_join

; __device__ __forceinline__ unsigned f2bf(float f) { unsigned u = __builtin_bit_cast(unsigned, f); return (u + 0x7fffu + ((u >> 16) & 1u)) >> 16; }
; template <bool SAMPLE> __device__ __forceinline__ void attn_unit16(const Ctx& c, LAS unsigned char* lds, int b, int h, int qb, int wave_s) {
;     ...
;     if (active && !mp) {
;         bf16* Y = (bf16*)(ws + WS_YD);
;         float sg[8];
; #pragma unroll
;         for (int et = 0; et < 8; ++et) sg[et] = c.subg[16 * et + c16b] * 0.8f;
; #pragma unroll
;         for (int qt = 0; qt < (SAMPLE ? 1 : 2); ++qt)
; #pragma unroll
;             for (int i = 0; i < 4; ++i) {
;                 float ss = 0.f;
; #pragma unroll
;                 for (int et = 0; et < 8; ++et) { o[qt][et][i] -= X[(g * 64 + qt * 32 + et * 4 + i) * 64 + lane2]; ss += o[qt][et][i] * o[qt][et][i]; }
;                 ss += __shfl_xor(ss, 1); ss += __shfl_xor(ss, 2); ss += __shfl_xor(ss, 4); ss += __shfl_xor(ss, 8);
;                 const float rstd = 1.f / sqrtf(ss * (1.f / 128.f) + 1e-5f);
;                 const int ql = 16 * qt + 4 * q4b + i;
;                 const size_t row = SAMPLE ? (size_t)ROW_S0 + b * 16 + ql : (size_t)b * SEQ + tq0 + ql;
; #pragma unroll
;                 for (int et = 0; et < 8; ++et) Y[row * D + h * 128 + 16 * et + c16b] = (bf16)f2bf(o[qt][et][i] * rstd * sg[et]);
.LBB0_886:
	s_andn2_b64 vcc, exec, s[2:3]
	s_waitcnt lgkmcnt(0)
	s_barrier
	s_cbranch_vccnz .LBB0_888
	s_lshl_b32 s0, s63, 14
	v_and_b32_e32 v49, 15, v7
	s_add_i32 s0, s0, 0
	v_lshlrev_b32_e32 v10, 2, v49
	v_lshl_add_u32 v64, v6, 2, s0
	ds_read2st64_b32 v[6:7], v64 offset1:1
	ds_read2st64_b32 v[8:9], v64 offset0:4 offset1:5
	ds_read2st64_b32 v[10:11], v64 offset0:6 offset1:7
	ds_read2st64_b32 v[12:13], v64 offset0:2 offset1:3
	ds_read2st64_b32 v[66:67], v64 offset0:8 offset1:9
	s_waitcnt lgkmcnt(4)
	v_sub_f32_e32 v6, v14, v6
	s_waitcnt lgkmcnt(3)
	v_sub_f32_e32 v8, v15, v8
	ds_read2st64_b32 v[76:77], v64 offset0:12 offset1:13
	ds_read2st64_b32 v[14:15], v64 offset0:14 offset1:15
	ds_read2st64_b32 v[16:17], v64 offset0:10 offset1:11
	ds_read2st64_b32 v[78:79], v64 offset0:16 offset1:17
	v_mul_f32_e32 v54, v8, v8
	s_waitcnt lgkmcnt(4)
	v_sub_f32_e32 v66, v19, v66
	s_waitcnt lgkmcnt(3)
	v_sub_f32_e32 v76, v18, v76
	ds_read2st64_b32 v[90:91], v64 offset0:20 offset1:21
	ds_read2st64_b32 v[18:19], v64 offset0:22 offset1:23
	ds_read2st64_b32 v[20:21], v64 offset0:18 offset1:19
	ds_read2st64_b32 v[96:97], v64 offset0:24 offset1:25
	v_fmac_f32_e32 v54, v6, v6
	v_fmac_f32_e32 v54, v66, v66
	v_fmac_f32_e32 v54, v76, v76
	s_waitcnt lgkmcnt(4)
	v_sub_f32_e32 v78, v5, v78
	ds_read2st64_b32 v[98:99], v64 offset0:28 offset1:29
	ds_read2st64_b32 v[22:23], v64 offset0:30 offset1:31
	ds_read2st64_b32 v[24:25], v64 offset0:26 offset1:27
	v_fmac_f32_e32 v54, v78, v78
	s_waitcnt lgkmcnt(6)
	v_sub_f32_e32 v90, v3, v90
	v_fmac_f32_e32 v54, v90, v90
	s_waitcnt lgkmcnt(3)
	v_sub_f32_e32 v96, v2, v96
	v_fmac_f32_e32 v54, v96, v96
	s_waitcnt lgkmcnt(2)
	v_sub_f32_e32 v98, v0, v98
	v_fmac_f32_e32 v54, v98, v98
	v_or_b32_e32 v4, s62, v4
	v_sub_f32_e32 v9, v114, v9
	v_sub_f32_e32 v67, v112, v67
	v_sub_f32_e32 v10, v92, v10
	s_waitcnt lgkmcnt(0)
	s_nop 1
	v_add_f32_dpp v0, v54, v54 quad_perm:[1,0,3,2] row_mask:0xf bank_mask:0xf
	v_sub_f32_e32 v12, v89, v12
	v_sub_f32_e32 v16, v88, v16
	v_sub_f32_e32 v14, v87, v14
	v_sub_f32_e32 v20, v86, v20
	s_waitcnt lgkmcnt(0)
	s_nop 1
	v_add_f32_dpp v0, v0, v0 quad_perm:[2,3,0,1] row_mask:0xf bank_mask:0xf
	v_sub_f32_e32 v18, v85, v18
	v_sub_f32_e32 v24, v84, v24
	v_sub_f32_e32 v22, v82, v22
	v_sub_f32_e32 v11, v81, v11
	s_waitcnt lgkmcnt(0)
	s_nop 1
	v_add_f32_dpp v0, v0, v0 row_half_mirror row_mask:0xf bank_mask:0xf
	v_sub_f32_e32 v15, v74, v15
	s_waitcnt lgkmcnt(0)
	s_nop 1
	v_add_f32_dpp v0, v0, v0 row_mirror row_mask:0xf bank_mask:0xf
	v_fmamk_f32 v0, v0, 0x3c000000, v205
	v_mul_f32_e32 v2, 0x4f800000, v0
	v_cmp_gt_f32_e32 vcc, s75, v0
	s_nop 1
	v_cndmask_b32_e32 v5, v0, v2, vcc
	v_sqrt_f32_e32 v54, v5
	v_lshlrev_b32_e32 v0, 1, v49
	v_lshl_add_u64 v[2:3], s[40:41], 0, v[0:1]
	v_add_u32_e32 v0, -1, v54
	v_add_u32_e32 v49, 1, v54
	v_fma_f32 v55, -v0, v54, v5
	v_fma_f32 v62, -v49, v54, v5
	v_cmp_ge_f32_e64 s[0:1], 0, v55
	s_waitcnt vmcnt(6)
	v_mul_f32_e32 v55, 0x3f4ccccd, v239
	v_cndmask_b32_e64 v0, v54, v0, s[0:1]
	v_cmp_lt_f32_e64 s[0:1], 0, v62
	s_waitcnt vmcnt(5)
	v_mul_f32_e32 v54, 0x3f4ccccd, v240
	s_waitcnt vmcnt(4)
	v_mul_f32_e32 v53, 0x3f4ccccd, v241
	v_cndmask_b32_e64 v0, v0, v49, s[0:1]
	v_mul_f32_e32 v49, 0x37800000, v0
	v_cndmask_b32_e32 v0, v0, v49, vcc
	v_cmp_class_f32_e32 vcc, v5, v206
	s_waitcnt vmcnt(3)
	v_mul_f32_e32 v51, 0x3f4ccccd, v242
	v_mul_f32_e32 v62, 0x3f4ccccd, v238
	v_cndmask_b32_e32 v5, v0, v5, vcc
	v_div_scale_f32 v102, s[0:1], v5, v5, 1.0
	v_rcp_f32_e32 v103, v102
	s_waitcnt vmcnt(2)
	v_mul_f32_e32 v50, 0x3f4ccccd, v243
	s_waitcnt vmcnt(1)
	v_mul_f32_e32 v49, 0x3f4ccccd, v244
	s_waitcnt vmcnt(0)
	v_mul_f32_e32 v0, 0x3f4ccccd, v245
	v_fma_f32 v65, -v102, v103, 1.0
	v_fmac_f32_e32 v103, v65, v103
	v_div_scale_f32 v65, vcc, 1.0, v5, 1.0
	v_mul_f32_e32 v71, v65, v103
	v_fma_f32 v83, -v102, v71, v65
	v_fmac_f32_e32 v71, v83, v103
	v_fma_f32 v65, -v102, v71, v65
	v_div_fmas_f32 v65, v65, v103, v71
	v_div_fixup_f32 v65, v65, v5, 1.0
	v_mul_f32_e32 v6, v6, v65
	v_mov_b32_e32 v5, s17
	v_mul_f32_e32 v6, v62, v6
	v_lshlrev_b64 v[100:101], 11, v[4:5]
	v_bfe_u32 v71, v6, 16, 1
	v_lshl_add_u64 v[100:101], v[2:3], 0, v[100:101]
	v_add3_u32 v6, v6, v71, s76
	global_store_short_d16_hi v[100:101], v6, off
	v_mul_f32_e32 v6, v8, v65
	v_mul_f32_e32 v6, v55, v6
	v_bfe_u32 v8, v6, 16, 1
	v_add3_u32 v6, v6, v8, s76
	global_store_short_d16_hi v[100:101], v6, off offset:32
	v_mul_f32_e32 v6, v66, v65
	v_mul_f32_e32 v6, v54, v6
	v_sub_f32_e32 v66, v113, v7
	v_mul_f32_e32 v7, v9, v9
	v_bfe_u32 v8, v6, 16, 1
	v_fmac_f32_e32 v7, v66, v66
	v_add3_u32 v6, v6, v8, s76
	v_fmac_f32_e32 v7, v67, v67
	v_sub_f32_e32 v71, v105, v77
	global_store_short_d16_hi v[100:101], v6, off offset:64
	v_mul_f32_e32 v6, v76, v65
	v_fmac_f32_e32 v7, v71, v71
	v_sub_f32_e32 v76, v104, v79
	v_fmac_f32_e32 v7, v76, v76
	v_sub_f32_e32 v77, v95, v91
	v_fmac_f32_e32 v7, v77, v77
	v_sub_f32_e32 v79, v94, v97
	v_fmac_f32_e32 v7, v79, v79
	v_sub_f32_e32 v83, v93, v99
	v_fmac_f32_e32 v7, v83, v83
	ds_bpermute_b32 v91, v210, v7
	v_mul_f32_e32 v6, v53, v6
	v_bfe_u32 v8, v6, 16, 1
	v_add3_u32 v6, v6, v8, s76
	global_store_short_d16_hi v[100:101], v6, off offset:96
	s_waitcnt lgkmcnt(0)
	v_add_f32_e32 v7, v7, v91
	v_mul_f32_e32 v6, v78, v65
	v_mul_f32_e32 v6, v51, v6
	v_bfe_u32 v78, v6, 16, 1
	v_add3_u32 v6, v6, v78, s76
	s_waitcnt lgkmcnt(0)
	s_nop 1
	v_add_f32_dpp v7, v7, v7 quad_perm:[2,3,0,1] row_mask:0xf bank_mask:0xf
	global_store_short_d16_hi v[100:101], v6, off offset:128
	v_mul_f32_e32 v6, v90, v65
	v_mul_f32_e32 v6, v50, v6
	v_bfe_u32 v78, v6, 16, 1
	v_add3_u32 v6, v6, v78, s76
	global_store_short_d16_hi v[100:101], v6, off offset:160
	s_waitcnt lgkmcnt(0)
; __device__ __forceinline__ unsigned f2bf(float f) { unsigned u = __builtin_bit_cast(unsigned, f); return (u + 0x7fffu + ((u >> 16) & 1u)) >> 16; }
; template <bool SAMPLE> __device__ __forceinline__ void attn_unit16(const Ctx& c, LAS unsigned char* lds, int b, int h, int qb, int wave_s) {
;     ...
;             for (int i = 0; i < 4; ++i) {
;                 float ss = 0.f;
; #pragma unroll
;                 for (int et = 0; et < 8; ++et) { o[qt][et][i] -= X[(g * 64 + qt * 32 + et * 4 + i) * 64 + lane2]; ss += o[qt][et][i] * o[qt][et][i]; }
;                 ss += __shfl_xor(ss, 1); ss += __shfl_xor(ss, 2); ss += __shfl_xor(ss, 4); ss += __shfl_xor(ss, 8);
;                 const float rstd = 1.f / sqrtf(ss * (1.f / 128.f) + 1e-5f);
;                 const int ql = 16 * qt + 4 * q4b + i;
;                 const size_t row = SAMPLE ? (size_t)ROW_S0 + b * 16 + ql : (size_t)b * SEQ + tq0 + ql;
; #pragma unroll
;                 for (int et = 0; et < 8; ++et) Y[row * D + h * 128 + 16 * et + c16b] = (bf16)f2bf(o[qt][et][i] * rstd * sg[et]);
	s_nop 1
	v_add_f32_dpp v6, v7, v7 row_half_mirror row_mask:0xf bank_mask:0xf
	v_mul_f32_e32 v8, v96, v65
	v_mul_f32_e32 v8, v49, v8
	v_bfe_u32 v78, v8, 16, 1
	v_add3_u32 v8, v8, v78, s76
	s_waitcnt lgkmcnt(0)
	s_nop 1
	v_add_f32_dpp v6, v6, v6 row_mirror row_mask:0xf bank_mask:0xf
	v_fmamk_f32 v6, v6, 0x3c000000, v205
	v_mul_f32_e32 v7, 0x4f800000, v6
	v_cmp_gt_f32_e32 vcc, s75, v6
	global_store_short_d16_hi v[100:101], v8, off offset:192
	v_mul_f32_e32 v8, v98, v65
	v_cndmask_b32_e32 v6, v6, v7, vcc
	v_sqrt_f32_e32 v7, v6
	v_mul_f32_e32 v8, v0, v8
	v_add_u32_e32 v65, -1, v7
	v_fma_f32 v78, -v65, v7, v6
	v_cmp_ge_f32_e64 s[0:1], 0, v78
	v_add_u32_e32 v78, 1, v7
	s_nop 0
	v_cndmask_b32_e64 v65, v7, v65, s[0:1]
	v_fma_f32 v7, -v78, v7, v6
	v_cmp_lt_f32_e64 s[0:1], 0, v7
	s_nop 1
	v_cndmask_b32_e64 v7, v65, v78, s[0:1]
	v_mul_f32_e32 v65, 0x37800000, v7
	v_cndmask_b32_e32 v7, v7, v65, vcc
	v_cmp_class_f32_e32 vcc, v6, v206
	v_bfe_u32 v78, v8, 16, 1
	v_add3_u32 v8, v8, v78, s76
	v_cndmask_b32_e32 v6, v7, v6, vcc
	v_div_scale_f32 v7, s[0:1], v6, v6, 1.0
	v_rcp_f32_e32 v65, v7
	global_store_short_d16_hi v[100:101], v8, off offset:224
	v_fma_f32 v8, -v7, v65, 1.0
	v_fmac_f32_e32 v65, v8, v65
	v_div_scale_f32 v8, vcc, 1.0, v6, 1.0
	v_mul_f32_e32 v78, v8, v65
	v_fma_f32 v90, -v7, v78, v8
	v_fmac_f32_e32 v78, v90, v65
	v_fma_f32 v7, -v7, v78, v8
	v_div_fmas_f32 v7, v7, v65, v78
	v_div_fixup_f32 v8, v7, v6, 1.0
	v_mul_f32_e32 v65, v66, v8
	v_mul_f32_e32 v65, v62, v65
	v_bfe_u32 v66, v65, 16, 1
	v_add3_u32 v65, v65, v66, s76
	v_mul_f32_e32 v66, v10, v10
	v_or_b32_e32 v6, 1, v4
	v_mov_b32_e32 v7, s17
	v_fmac_f32_e32 v66, v12, v12
	v_lshlrev_b64 v[6:7], 11, v[6:7]
	v_mul_f32_e32 v9, v9, v8
	v_fmac_f32_e32 v66, v16, v16
	v_lshl_add_u64 v[6:7], v[2:3], 0, v[6:7]
	v_mul_f32_e32 v9, v55, v9
	v_fmac_f32_e32 v66, v14, v14
	global_store_short_d16_hi v[6:7], v65, off
	v_bfe_u32 v65, v9, 16, 1
	v_fmac_f32_e32 v66, v20, v20
	v_add3_u32 v9, v9, v65, s76
	v_fmac_f32_e32 v66, v18, v18
	global_store_short_d16_hi v[6:7], v9, off offset:32
	v_mul_f32_e32 v9, v67, v8
	v_fmac_f32_e32 v66, v24, v24
	v_mul_f32_e32 v9, v54, v9
	v_fmac_f32_e32 v66, v22, v22
	v_bfe_u32 v65, v9, 16, 1
	v_add3_u32 v9, v9, v65, s76
	global_store_short_d16_hi v[6:7], v9, off offset:64
	v_mul_f32_e32 v9, v71, v8
	v_mul_f32_e32 v9, v53, v9
	v_bfe_u32 v65, v9, 16, 1
	v_add3_u32 v9, v9, v65, s76
	s_waitcnt lgkmcnt(0)
	s_nop 1
	v_add_f32_dpp v65, v66, v66 quad_perm:[1,0,3,2] row_mask:0xf bank_mask:0xf
	global_store_short_d16_hi v[6:7], v9, off offset:96
	v_mul_f32_e32 v9, v76, v8
	v_mul_f32_e32 v9, v51, v9
	v_bfe_u32 v67, v9, 16, 1
	s_waitcnt lgkmcnt(0)
	s_nop 1
	v_add_f32_dpp v65, v65, v65 quad_perm:[2,3,0,1] row_mask:0xf bank_mask:0xf
	v_add3_u32 v9, v9, v67, s76
	global_store_short_d16_hi v[6:7], v9, off offset:128
	v_mul_f32_e32 v9, v77, v8
	v_mul_f32_e32 v9, v50, v9
	v_bfe_u32 v67, v9, 16, 1
	v_add3_u32 v9, v9, v67, s76
	global_store_short_d16_hi v[6:7], v9, off offset:160
	s_waitcnt lgkmcnt(0)
	s_nop 1
	v_add_f32_dpp v9, v65, v65 row_half_mirror row_mask:0xf bank_mask:0xf
	v_mul_f32_e32 v66, v79, v8
	v_mul_f32_e32 v66, v49, v66
	v_bfe_u32 v67, v66, 16, 1
	v_add3_u32 v66, v66, v67, s76
	s_waitcnt lgkmcnt(0)
	s_nop 1
	v_add_f32_dpp v9, v9, v9 row_mirror row_mask:0xf bank_mask:0xf
	v_fmamk_f32 v9, v9, 0x3c000000, v205
	v_mul_f32_e32 v65, 0x4f800000, v9
	v_cmp_gt_f32_e32 vcc, s75, v9
	global_store_short_d16_hi v[6:7], v66, off offset:192
	v_mul_f32_e32 v8, v83, v8
	v_cndmask_b32_e32 v9, v9, v65, vcc
	v_sqrt_f32_e32 v65, v9
	v_mul_f32_e32 v8, v0, v8
	v_sub_f32_e32 v76, v72, v19
	v_sub_f32_e32 v77, v70, v25
	v_add_u32_e32 v66, -1, v65
	v_fma_f32 v67, -v66, v65, v9
	v_cmp_ge_f32_e64 s[0:1], 0, v67
	v_add_u32_e32 v67, 1, v65
	v_sub_f32_e32 v78, v69, v23
	v_cndmask_b32_e64 v66, v65, v66, s[0:1]
	v_fma_f32 v65, -v67, v65, v9
	v_cmp_lt_f32_e64 s[0:1], 0, v65
	s_nop 1
	v_cndmask_b32_e64 v65, v66, v67, s[0:1]
	v_mul_f32_e32 v66, 0x37800000, v65
	v_cndmask_b32_e32 v65, v65, v66, vcc
	v_cmp_class_f32_e32 vcc, v9, v206
	v_bfe_u32 v67, v8, 16, 1
	v_add3_u32 v8, v8, v67, s76
	v_cndmask_b32_e32 v9, v65, v9, vcc
	v_div_scale_f32 v65, s[0:1], v9, v9, 1.0
	v_rcp_f32_e32 v66, v65
	global_store_short_d16_hi v[6:7], v8, off offset:224
	v_fma_f32 v6, -v65, v66, 1.0
	v_fmac_f32_e32 v66, v6, v66
	v_div_scale_f32 v6, vcc, 1.0, v9, 1.0
	v_mul_f32_e32 v7, v6, v66
	v_fma_f32 v8, -v65, v7, v6
	v_fmac_f32_e32 v7, v8, v66
	v_fma_f32 v6, -v65, v7, v6
	v_div_fmas_f32 v6, v6, v66, v7
	v_div_fixup_f32 v8, v6, v9, 1.0
	v_mul_f32_e32 v9, v12, v8
	v_or_b32_e32 v6, 2, v4
	v_mov_b32_e32 v7, s17
	v_mul_f32_e32 v9, v62, v9
	v_lshlrev_b64 v[6:7], 11, v[6:7]
	v_bfe_u32 v12, v9, 16, 1
	v_lshl_add_u64 v[6:7], v[2:3], 0, v[6:7]
	v_add3_u32 v9, v9, v12, s76
	global_store_short_d16_hi v[6:7], v9, off
	v_mul_f32_e32 v9, v10, v8
	v_mul_f32_e32 v9, v55, v9
	v_bfe_u32 v10, v9, 16, 1
	v_add3_u32 v9, v9, v10, s76
	global_store_short_d16_hi v[6:7], v9, off offset:32
	v_mul_f32_e32 v9, v16, v8
	v_mul_f32_e32 v9, v54, v9
	v_bfe_u32 v10, v9, 16, 1
	v_add3_u32 v9, v9, v10, s76
	v_sub_f32_e32 v12, v80, v13
	v_mul_f32_e32 v13, v11, v11
	global_store_short_d16_hi v[6:7], v9, off offset:64
	v_mul_f32_e32 v9, v14, v8
	v_fmac_f32_e32 v13, v12, v12
	v_sub_f32_e32 v14, v75, v17
	v_fmac_f32_e32 v13, v14, v14
	v_fmac_f32_e32 v13, v15, v15
	v_sub_f32_e32 v65, v73, v21
	v_fmac_f32_e32 v13, v65, v65
	v_fmac_f32_e32 v13, v76, v76
	v_fmac_f32_e32 v13, v77, v77
	v_fmac_f32_e32 v13, v78, v78
	v_mul_f32_e32 v9, v53, v9
	v_bfe_u32 v10, v9, 16, 1
	v_add3_u32 v9, v9, v10, s76
	global_store_short_d16_hi v[6:7], v9, off offset:96
	s_waitcnt lgkmcnt(0)
; __device__ __forceinline__ unsigned f2bf(float f) { unsigned u = __builtin_bit_cast(unsigned, f); return (u + 0x7fffu + ((u >> 16) & 1u)) >> 16; }
; template <bool SAMPLE> __device__ __forceinline__ void attn_unit16(const Ctx& c, LAS unsigned char* lds, int b, int h, int qb, int wave_s) {
;     ...
;             for (int i = 0; i < 4; ++i) {
;                 float ss = 0.f;
; #pragma unroll
;                 for (int et = 0; et < 8; ++et) { o[qt][et][i] -= X[(g * 64 + qt * 32 + et * 4 + i) * 64 + lane2]; ss += o[qt][et][i] * o[qt][et][i]; }
;                 ss += __shfl_xor(ss, 1); ss += __shfl_xor(ss, 2); ss += __shfl_xor(ss, 4); ss += __shfl_xor(ss, 8);
;                 const float rstd = 1.f / sqrtf(ss * (1.f / 128.f) + 1e-5f);
;                 const int ql = 16 * qt + 4 * q4b + i;
;                 const size_t row = SAMPLE ? (size_t)ROW_S0 + b * 16 + ql : (size_t)b * SEQ + tq0 + ql;
; #pragma unroll
;                 for (int et = 0; et < 8; ++et) Y[row * D + h * 128 + 16 * et + c16b] = (bf16)f2bf(o[qt][et][i] * rstd * sg[et]);
	s_nop 1
	v_add_f32_dpp v10, v13, v13 quad_perm:[1,0,3,2] row_mask:0xf bank_mask:0xf
	v_mul_f32_e32 v9, v20, v8
	v_mul_f32_e32 v9, v51, v9
	v_bfe_u32 v16, v9, 16, 1
	v_add3_u32 v9, v9, v16, s76
	s_waitcnt lgkmcnt(0)
	s_nop 1
	v_add_f32_dpp v10, v10, v10 quad_perm:[2,3,0,1] row_mask:0xf bank_mask:0xf
	global_store_short_d16_hi v[6:7], v9, off offset:128
	v_mul_f32_e32 v9, v18, v8
	v_mul_f32_e32 v9, v50, v9
	v_bfe_u32 v16, v9, 16, 1
	v_add3_u32 v9, v9, v16, s76
	global_store_short_d16_hi v[6:7], v9, off offset:160
	s_waitcnt lgkmcnt(0)
	s_nop 1
	v_add_f32_dpp v9, v10, v10 row_half_mirror row_mask:0xf bank_mask:0xf
	v_mul_f32_e32 v13, v24, v8
	v_mul_f32_e32 v13, v49, v13
	v_bfe_u32 v16, v13, 16, 1
	v_add3_u32 v13, v13, v16, s76
	s_waitcnt lgkmcnt(0)
	s_nop 1
	v_add_f32_dpp v9, v9, v9 row_mirror row_mask:0xf bank_mask:0xf
	v_fmamk_f32 v9, v9, 0x3c000000, v205
	v_mul_f32_e32 v10, 0x4f800000, v9
	v_cmp_gt_f32_e32 vcc, s75, v9
	global_store_short_d16_hi v[6:7], v13, off offset:192
	v_mul_f32_e32 v8, v22, v8
	v_cndmask_b32_e32 v9, v9, v10, vcc
	v_sqrt_f32_e32 v10, v9
	v_mul_f32_e32 v8, v0, v8
	v_add_u32_e32 v13, -1, v10
	v_fma_f32 v16, -v13, v10, v9
	v_cmp_ge_f32_e64 s[0:1], 0, v16
	v_add_u32_e32 v16, 1, v10
	s_nop 0
	v_cndmask_b32_e64 v13, v10, v13, s[0:1]
	v_fma_f32 v10, -v16, v10, v9
	v_cmp_lt_f32_e64 s[0:1], 0, v10
	s_nop 1
	v_cndmask_b32_e64 v10, v13, v16, s[0:1]
	v_mul_f32_e32 v13, 0x37800000, v10
	v_cndmask_b32_e32 v10, v10, v13, vcc
	v_cmp_class_f32_e32 vcc, v9, v206
	v_bfe_u32 v16, v8, 16, 1
	v_add3_u32 v8, v8, v16, s76
	v_cndmask_b32_e32 v9, v10, v9, vcc
	v_div_scale_f32 v10, s[0:1], v9, v9, 1.0
	v_rcp_f32_e32 v13, v10
	global_store_short_d16_hi v[6:7], v8, off offset:224
	v_fma_f32 v6, -v10, v13, 1.0
	v_fmac_f32_e32 v13, v6, v13
	v_div_scale_f32 v6, vcc, 1.0, v9, 1.0
	v_mul_f32_e32 v7, v6, v13
	v_fma_f32 v8, -v10, v7, v6
	v_fmac_f32_e32 v7, v8, v13
	v_fma_f32 v6, -v10, v7, v6
	v_div_fmas_f32 v6, v6, v13, v7
	v_div_fixup_f32 v79, v6, v9, 1.0
	v_mul_f32_e32 v8, v12, v79
	v_or_b32_e32 v6, 3, v4
	v_mov_b32_e32 v7, s17
	v_mul_f32_e32 v8, v62, v8
	v_lshlrev_b64 v[6:7], 11, v[6:7]
	v_bfe_u32 v9, v8, 16, 1
	v_lshl_add_u64 v[6:7], v[2:3], 0, v[6:7]
	v_add3_u32 v8, v8, v9, s76
	global_store_short_d16_hi v[6:7], v8, off
	v_mul_f32_e32 v8, v11, v79
	v_mul_f32_e32 v8, v55, v8
	v_bfe_u32 v9, v8, 16, 1
	v_add3_u32 v8, v8, v9, s76
	global_store_short_d16_hi v[6:7], v8, off offset:32
	v_mul_f32_e32 v8, v14, v79
	v_mul_f32_e32 v8, v54, v8
	v_bfe_u32 v9, v8, 16, 1
	v_add3_u32 v8, v8, v9, s76
	global_store_short_d16_hi v[6:7], v8, off offset:64
	v_mul_f32_e32 v8, v15, v79
	v_mul_f32_e32 v80, v53, v8
	ds_read2st64_b32 v[8:9], v64 offset0:32 offset1:33
	ds_read2st64_b32 v[10:11], v64 offset0:36 offset1:37
	ds_read2st64_b32 v[12:13], v64 offset0:38 offset1:39
	ds_read2st64_b32 v[14:15], v64 offset0:34 offset1:35
	ds_read2st64_b32 v[66:67], v64 offset0:40 offset1:41
	v_bfe_u32 v81, v80, 16, 1
	s_waitcnt lgkmcnt(4)
	v_sub_f32_e32 v8, v63, v8
	s_waitcnt lgkmcnt(3)
	v_sub_f32_e32 v10, v68, v10
	ds_read2st64_b32 v[68:69], v64 offset0:44 offset1:45
	ds_read2st64_b32 v[16:17], v64 offset0:46 offset1:47
	ds_read2st64_b32 v[18:19], v64 offset0:42 offset1:43
	s_waitcnt lgkmcnt(3)
	v_sub_f32_e32 v66, v61, v66
	v_mul_f32_e32 v63, v10, v10
	s_waitcnt lgkmcnt(2)
	v_sub_f32_e32 v68, v60, v68
	ds_read2st64_b32 v[60:61], v64 offset0:48 offset1:49
	ds_read2st64_b32 v[70:71], v64 offset0:52 offset1:53
	ds_read2st64_b32 v[20:21], v64 offset0:54 offset1:55
	ds_read2st64_b32 v[22:23], v64 offset0:50 offset1:51
	ds_read2st64_b32 v[72:73], v64 offset0:56 offset1:57
	v_fmac_f32_e32 v63, v8, v8
	v_fmac_f32_e32 v63, v66, v66
	v_fmac_f32_e32 v63, v68, v68
	s_waitcnt lgkmcnt(4)
	v_sub_f32_e32 v60, v27, v60
	s_waitcnt lgkmcnt(3)
	v_sub_f32_e32 v70, v26, v70
	ds_read2st64_b32 v[74:75], v64 offset0:60 offset1:61
	ds_read2st64_b32 v[24:25], v64 offset0:62 offset1:63
	ds_read2st64_b32 v[26:27], v64 offset0:58 offset1:59
	v_fmac_f32_e32 v63, v60, v60
	v_fmac_f32_e32 v63, v70, v70
	s_waitcnt lgkmcnt(3)
	v_sub_f32_e32 v59, v59, v72
	v_fmac_f32_e32 v63, v59, v59
	s_waitcnt lgkmcnt(2)
	v_sub_f32_e32 v58, v58, v74
	v_fmac_f32_e32 v63, v58, v58
	v_mul_f32_e32 v65, v65, v79
	v_add3_u32 v72, v80, v81, s76
	v_mul_f32_e32 v65, v51, v65
	global_store_short_d16_hi v[6:7], v72, off offset:96
	s_waitcnt lgkmcnt(0)
	s_nop 1
	v_add_f32_dpp v63, v63, v63 quad_perm:[1,0,3,2] row_mask:0xf bank_mask:0xf
	v_bfe_u32 v72, v65, 16, 1
	v_add3_u32 v65, v65, v72, s76
	global_store_short_d16_hi v[6:7], v65, off offset:128
	v_mul_f32_e32 v65, v76, v79
	s_waitcnt lgkmcnt(0)
	s_nop 1
	v_add_f32_dpp v63, v63, v63 quad_perm:[2,3,0,1] row_mask:0xf bank_mask:0xf
	v_mul_f32_e32 v65, v50, v65
	v_bfe_u32 v72, v65, 16, 1
	v_add3_u32 v65, v65, v72, s76
	global_store_short_d16_hi v[6:7], v65, off offset:160
	s_waitcnt lgkmcnt(0)
	s_nop 1
	v_add_f32_dpp v63, v63, v63 row_half_mirror row_mask:0xf bank_mask:0xf
	v_mul_f32_e32 v65, v77, v79
	v_mul_f32_e32 v65, v49, v65
	v_bfe_u32 v72, v65, 16, 1
	v_add3_u32 v65, v65, v72, s76
	s_waitcnt lgkmcnt(0)
; __device__ __forceinline__ unsigned f2bf(float f) { unsigned u = __builtin_bit_cast(unsigned, f); return (u + 0x7fffu + ((u >> 16) & 1u)) >> 16; }
; template <bool SAMPLE> __device__ __forceinline__ void attn_unit16(const Ctx& c, LAS unsigned char* lds, int b, int h, int qb, int wave_s) {
;     ...
;         for (int qt = 0; qt < (SAMPLE ? 1 : 2); ++qt)
; #pragma unroll
;             for (int i = 0; i < 4; ++i) {
;                 float ss = 0.f;
; #pragma unroll
;                 for (int et = 0; et < 8; ++et) { o[qt][et][i] -= X[(g * 64 + qt * 32 + et * 4 + i) * 64 + lane2]; ss += o[qt][et][i] * o[qt][et][i]; }
;                 ss += __shfl_xor(ss, 1); ss += __shfl_xor(ss, 2); ss += __shfl_xor(ss, 4); ss += __shfl_xor(ss, 8);
;                 const float rstd = 1.f / sqrtf(ss * (1.f / 128.f) + 1e-5f);
;                 const int ql = 16 * qt + 4 * q4b + i;
;                 const size_t row = SAMPLE ? (size_t)ROW_S0 + b * 16 + ql : (size_t)b * SEQ + tq0 + ql;
; #pragma unroll
;                 for (int et = 0; et < 8; ++et) Y[row * D + h * 128 + 16 * et + c16b] = (bf16)f2bf(o[qt][et][i] * rstd * sg[et]);
;             }
	s_nop 1
	v_add_f32_dpp v63, v63, v63 row_mirror row_mask:0xf bank_mask:0xf
	v_fmamk_f32 v63, v63, 0x3c000000, v205
	v_mul_f32_e32 v64, 0x4f800000, v63
	v_cmp_gt_f32_e32 vcc, s75, v63
	global_store_short_d16_hi v[6:7], v65, off offset:192
	v_mul_f32_e32 v65, v78, v79
	v_cndmask_b32_e32 v63, v63, v64, vcc
	v_sqrt_f32_e32 v64, v63
	v_mul_f32_e32 v65, v0, v65
	v_sub_f32_e32 v11, v52, v11
	v_sub_f32_e32 v9, v48, v9
	v_add_u32_e32 v72, -1, v64
	v_fma_f32 v74, -v72, v64, v63
	v_cmp_ge_f32_e64 s[0:1], 0, v74
	v_add_u32_e32 v74, 1, v64
	v_mul_f32_e32 v48, v11, v11
	v_cndmask_b32_e64 v72, v64, v72, s[0:1]
	v_fma_f32 v64, -v74, v64, v63
	v_cmp_lt_f32_e64 s[0:1], 0, v64
	v_fmac_f32_e32 v48, v9, v9
	v_sub_f32_e32 v45, v45, v67
	v_cndmask_b32_e64 v64, v72, v74, s[0:1]
	v_mul_f32_e32 v72, 0x37800000, v64
	v_cndmask_b32_e32 v64, v64, v72, vcc
	v_cmp_class_f32_e32 vcc, v63, v206
	v_bfe_u32 v74, v65, 16, 1
	v_add3_u32 v65, v65, v74, s76
	v_cndmask_b32_e32 v63, v64, v63, vcc
	v_div_scale_f32 v64, s[0:1], v63, v63, 1.0
	v_rcp_f32_e32 v72, v64
	global_store_short_d16_hi v[6:7], v65, off offset:224
	v_fmac_f32_e32 v48, v45, v45
	v_sub_f32_e32 v44, v44, v69
	v_fma_f32 v6, -v64, v72, 1.0
	v_fmac_f32_e32 v72, v6, v72
	v_div_scale_f32 v6, vcc, 1.0, v63, 1.0
	v_mul_f32_e32 v7, v6, v72
	v_fma_f32 v65, -v64, v7, v6
	v_fmac_f32_e32 v7, v65, v72
	v_fma_f32 v6, -v64, v7, v6
	v_div_fmas_f32 v6, v6, v72, v7
	v_div_fixup_f32 v63, v6, v63, 1.0
	v_mul_f32_e32 v8, v8, v63
	v_or_b32_e32 v6, 16, v4
	v_mov_b32_e32 v7, s17
	v_mul_f32_e32 v8, v62, v8
	v_lshlrev_b64 v[6:7], 11, v[6:7]
	v_bfe_u32 v64, v8, 16, 1
	v_lshl_add_u64 v[6:7], v[2:3], 0, v[6:7]
	v_add3_u32 v8, v8, v64, s76
	global_store_short_d16_hi v[6:7], v8, off
	v_mul_f32_e32 v8, v10, v63
	v_mul_f32_e32 v8, v55, v8
	v_fmac_f32_e32 v48, v44, v44
	v_sub_f32_e32 v52, v57, v61
	v_bfe_u32 v10, v8, 16, 1
	v_fmac_f32_e32 v48, v52, v52
	v_sub_f32_e32 v56, v56, v71
	v_add3_u32 v8, v8, v10, s76
	v_fmac_f32_e32 v48, v56, v56
	v_sub_f32_e32 v47, v47, v73
	global_store_short_d16_hi v[6:7], v8, off offset:32
	v_mul_f32_e32 v8, v66, v63
	v_fmac_f32_e32 v48, v47, v47
	v_sub_f32_e32 v46, v46, v75
	v_mul_f32_e32 v8, v54, v8
	v_fmac_f32_e32 v48, v46, v46
	v_bfe_u32 v10, v8, 16, 1
	v_add3_u32 v8, v8, v10, s76
	global_store_short_d16_hi v[6:7], v8, off offset:64
	v_mul_f32_e32 v8, v68, v63
	v_mul_f32_e32 v8, v53, v8
	v_bfe_u32 v10, v8, 16, 1
	v_add3_u32 v8, v8, v10, s76
	s_waitcnt lgkmcnt(0)
	s_nop 1
	v_add_f32_dpp v10, v48, v48 quad_perm:[1,0,3,2] row_mask:0xf bank_mask:0xf
	global_store_short_d16_hi v[6:7], v8, off offset:96
	v_mul_f32_e32 v8, v60, v63
	v_mul_f32_e32 v8, v51, v8
	v_bfe_u32 v57, v8, 16, 1
	s_waitcnt lgkmcnt(0)
	s_nop 1
	v_add_f32_dpp v10, v10, v10 quad_perm:[2,3,0,1] row_mask:0xf bank_mask:0xf
	v_add3_u32 v8, v8, v57, s76
	global_store_short_d16_hi v[6:7], v8, off offset:128
	v_mul_f32_e32 v8, v70, v63
	v_mul_f32_e32 v8, v50, v8
	v_bfe_u32 v57, v8, 16, 1
	v_add3_u32 v8, v8, v57, s76
	global_store_short_d16_hi v[6:7], v8, off offset:160
	s_waitcnt lgkmcnt(0)
	s_nop 1
	v_add_f32_dpp v8, v10, v10 row_half_mirror row_mask:0xf bank_mask:0xf
	v_mul_f32_e32 v48, v59, v63
	v_mul_f32_e32 v48, v49, v48
	v_bfe_u32 v57, v48, 16, 1
	v_add3_u32 v48, v48, v57, s76
	s_waitcnt lgkmcnt(0)
	s_nop 1
	v_add_f32_dpp v8, v8, v8 row_mirror row_mask:0xf bank_mask:0xf
	v_fmamk_f32 v8, v8, 0x3c000000, v205
	v_mul_f32_e32 v10, 0x4f800000, v8
	v_cmp_gt_f32_e32 vcc, s75, v8
	global_store_short_d16_hi v[6:7], v48, off offset:192
	v_mul_f32_e32 v48, v58, v63
	v_cndmask_b32_e32 v8, v8, v10, vcc
	v_sqrt_f32_e32 v10, v8
	v_mul_f32_e32 v48, v0, v48
	v_sub_f32_e32 v12, v41, v12
	v_sub_f32_e32 v18, v37, v18
	v_add_u32_e32 v57, -1, v10
	v_fma_f32 v58, -v57, v10, v8
	v_cmp_ge_f32_e64 s[0:1], 0, v58
	v_add_u32_e32 v58, 1, v10
	v_sub_f32_e32 v16, v36, v16
	v_cndmask_b32_e64 v57, v10, v57, s[0:1]
	v_fma_f32 v10, -v58, v10, v8
	v_cmp_lt_f32_e64 s[0:1], 0, v10
	v_sub_f32_e32 v22, v43, v22
	v_sub_f32_e32 v20, v42, v20
	v_cndmask_b32_e64 v10, v57, v58, s[0:1]
	v_mul_f32_e32 v57, 0x37800000, v10
	v_cndmask_b32_e32 v10, v10, v57, vcc
	v_cmp_class_f32_e32 vcc, v8, v206
	v_bfe_u32 v58, v48, 16, 1
	v_add3_u32 v48, v48, v58, s76
	v_cndmask_b32_e32 v8, v10, v8, vcc
	v_div_scale_f32 v10, s[0:1], v8, v8, 1.0
	v_rcp_f32_e32 v57, v10
	global_store_short_d16_hi v[6:7], v48, off offset:224
	v_sub_f32_e32 v26, v39, v26
	v_sub_f32_e32 v24, v38, v24
	v_fma_f32 v6, -v10, v57, 1.0
	v_fmac_f32_e32 v57, v6, v57
	v_div_scale_f32 v6, vcc, 1.0, v8, 1.0
	v_mul_f32_e32 v7, v6, v57
	v_fma_f32 v48, -v10, v7, v6
	v_fmac_f32_e32 v7, v48, v57
	v_fma_f32 v6, -v10, v7, v6
	v_div_fmas_f32 v6, v6, v57, v7
	v_div_fixup_f32 v8, v6, v8, 1.0
	v_mul_f32_e32 v9, v9, v8
	v_or_b32_e32 v6, 17, v4
	v_mov_b32_e32 v7, s17
	v_mul_f32_e32 v9, v62, v9
	v_lshlrev_b64 v[6:7], 11, v[6:7]
	v_bfe_u32 v10, v9, 16, 1
	v_lshl_add_u64 v[6:7], v[2:3], 0, v[6:7]
	v_add3_u32 v9, v9, v10, s76
	global_store_short_d16_hi v[6:7], v9, off
	v_mul_f32_e32 v9, v11, v8
	v_sub_f32_e32 v11, v40, v14
	v_mul_f32_e32 v14, v12, v12
	v_fmac_f32_e32 v14, v11, v11
	v_fmac_f32_e32 v14, v18, v18
	v_mul_f32_e32 v9, v55, v9
	v_fmac_f32_e32 v14, v16, v16
	v_bfe_u32 v10, v9, 16, 1
	v_fmac_f32_e32 v14, v22, v22
	v_add3_u32 v9, v9, v10, s76
	v_fmac_f32_e32 v14, v20, v20
	global_store_short_d16_hi v[6:7], v9, off offset:32
	v_mul_f32_e32 v9, v45, v8
	v_fmac_f32_e32 v14, v26, v26
	v_mul_f32_e32 v9, v54, v9
	v_fmac_f32_e32 v14, v24, v24
	v_bfe_u32 v10, v9, 16, 1
	v_add3_u32 v9, v9, v10, s76
	global_store_short_d16_hi v[6:7], v9, off offset:64
	v_mul_f32_e32 v9, v44, v8
	v_mul_f32_e32 v9, v53, v9
	v_bfe_u32 v10, v9, 16, 1
	v_add3_u32 v9, v9, v10, s76
	s_waitcnt lgkmcnt(0)
; __device__ __forceinline__ unsigned f2bf(float f) { unsigned u = __builtin_bit_cast(unsigned, f); return (u + 0x7fffu + ((u >> 16) & 1u)) >> 16; }
; template <bool SAMPLE> __device__ __forceinline__ void attn_unit16(const Ctx& c, LAS unsigned char* lds, int b, int h, int qb, int wave_s) {
;     ...
;         for (int qt = 0; qt < (SAMPLE ? 1 : 2); ++qt)
; #pragma unroll
;             for (int i = 0; i < 4; ++i) {
;                 float ss = 0.f;
; #pragma unroll
;                 for (int et = 0; et < 8; ++et) { o[qt][et][i] -= X[(g * 64 + qt * 32 + et * 4 + i) * 64 + lane2]; ss += o[qt][et][i] * o[qt][et][i]; }
;                 ss += __shfl_xor(ss, 1); ss += __shfl_xor(ss, 2); ss += __shfl_xor(ss, 4); ss += __shfl_xor(ss, 8);
;                 const float rstd = 1.f / sqrtf(ss * (1.f / 128.f) + 1e-5f);
;                 const int ql = 16 * qt + 4 * q4b + i;
;                 const size_t row = SAMPLE ? (size_t)ROW_S0 + b * 16 + ql : (size_t)b * SEQ + tq0 + ql;
; #pragma unroll
;                 for (int et = 0; et < 8; ++et) Y[row * D + h * 128 + 16 * et + c16b] = (bf16)f2bf(o[qt][et][i] * rstd * sg[et]);
;             }
	s_nop 1
	v_add_f32_dpp v10, v14, v14 quad_perm:[1,0,3,2] row_mask:0xf bank_mask:0xf
	global_store_short_d16_hi v[6:7], v9, off offset:96
	v_mul_f32_e32 v9, v52, v8
	v_mul_f32_e32 v9, v51, v9
	v_bfe_u32 v36, v9, 16, 1
	s_waitcnt lgkmcnt(0)
	s_nop 1
	v_add_f32_dpp v10, v10, v10 quad_perm:[2,3,0,1] row_mask:0xf bank_mask:0xf
	v_add3_u32 v9, v9, v36, s76
	global_store_short_d16_hi v[6:7], v9, off offset:128
	v_mul_f32_e32 v9, v56, v8
	v_mul_f32_e32 v9, v50, v9
	v_bfe_u32 v36, v9, 16, 1
	v_add3_u32 v9, v9, v36, s76
	global_store_short_d16_hi v[6:7], v9, off offset:160
	s_waitcnt lgkmcnt(0)
	s_nop 1
	v_add_f32_dpp v9, v10, v10 row_half_mirror row_mask:0xf bank_mask:0xf
	v_mul_f32_e32 v14, v47, v8
	v_mul_f32_e32 v14, v49, v14
	v_bfe_u32 v36, v14, 16, 1
	v_add3_u32 v14, v14, v36, s76
	s_waitcnt lgkmcnt(0)
	s_nop 1
	v_add_f32_dpp v9, v9, v9 row_mirror row_mask:0xf bank_mask:0xf
	v_fmamk_f32 v9, v9, 0x3c000000, v205
	v_mul_f32_e32 v10, 0x4f800000, v9
	v_cmp_gt_f32_e32 vcc, s75, v9
	global_store_short_d16_hi v[6:7], v14, off offset:192
	v_mul_f32_e32 v8, v46, v8
	v_cndmask_b32_e32 v9, v9, v10, vcc
	v_sqrt_f32_e32 v10, v9
	v_mul_f32_e32 v8, v0, v8
	v_add_u32_e32 v14, -1, v10
	v_fma_f32 v36, -v14, v10, v9
	v_cmp_ge_f32_e64 s[0:1], 0, v36
	v_add_u32_e32 v36, 1, v10
	s_nop 0
	v_cndmask_b32_e64 v14, v10, v14, s[0:1]
	v_fma_f32 v10, -v36, v10, v9
	v_cmp_lt_f32_e64 s[0:1], 0, v10
	s_nop 1
	v_cndmask_b32_e64 v10, v14, v36, s[0:1]
	v_mul_f32_e32 v14, 0x37800000, v10
	v_cndmask_b32_e32 v10, v10, v14, vcc
	v_cmp_class_f32_e32 vcc, v9, v206
	v_bfe_u32 v36, v8, 16, 1
	v_add3_u32 v8, v8, v36, s76
	v_cndmask_b32_e32 v9, v10, v9, vcc
	v_div_scale_f32 v10, s[0:1], v9, v9, 1.0
	v_rcp_f32_e32 v14, v10
	global_store_short_d16_hi v[6:7], v8, off offset:224
	v_fma_f32 v6, -v10, v14, 1.0
	v_fmac_f32_e32 v14, v6, v14
	v_div_scale_f32 v6, vcc, 1.0, v9, 1.0
	v_mul_f32_e32 v7, v6, v14
	v_fma_f32 v8, -v10, v7, v6
	v_fmac_f32_e32 v7, v8, v14
	v_fma_f32 v6, -v10, v7, v6
	v_div_fmas_f32 v6, v6, v14, v7
	v_div_fixup_f32 v8, v6, v9, 1.0
	v_mul_f32_e32 v9, v11, v8
	v_or_b32_e32 v6, 18, v4
	v_mov_b32_e32 v7, s17
	v_mul_f32_e32 v9, v62, v9
	v_lshlrev_b64 v[6:7], 11, v[6:7]
	v_bfe_u32 v10, v9, 16, 1
	v_lshl_add_u64 v[6:7], v[2:3], 0, v[6:7]
	v_add3_u32 v9, v9, v10, s76
	global_store_short_d16_hi v[6:7], v9, off
	v_mul_f32_e32 v9, v12, v8
	v_mul_f32_e32 v9, v55, v9
	v_bfe_u32 v10, v9, 16, 1
	v_add3_u32 v9, v9, v10, s76
	global_store_short_d16_hi v[6:7], v9, off offset:32
	v_mul_f32_e32 v9, v18, v8
	v_sub_f32_e32 v12, v35, v13
	v_mul_f32_e32 v9, v54, v9
	v_sub_f32_e32 v11, v34, v15
	v_mul_f32_e32 v13, v12, v12
	v_bfe_u32 v10, v9, 16, 1
	v_fmac_f32_e32 v13, v11, v11
	v_sub_f32_e32 v14, v33, v19
	v_add3_u32 v9, v9, v10, s76
	v_fmac_f32_e32 v13, v14, v14
	v_sub_f32_e32 v15, v32, v17
	global_store_short_d16_hi v[6:7], v9, off offset:64
	v_mul_f32_e32 v9, v16, v8
	v_fmac_f32_e32 v13, v15, v15
	v_sub_f32_e32 v16, v31, v23
	v_fmac_f32_e32 v13, v16, v16
	v_sub_f32_e32 v17, v30, v21
	v_fmac_f32_e32 v13, v17, v17
	v_sub_f32_e32 v18, v29, v27
	v_fmac_f32_e32 v13, v18, v18
	v_sub_f32_e32 v19, v28, v25
	v_fmac_f32_e32 v13, v19, v19
	v_mul_f32_e32 v9, v53, v9
	v_bfe_u32 v10, v9, 16, 1
	v_add3_u32 v9, v9, v10, s76
	global_store_short_d16_hi v[6:7], v9, off offset:96
	s_waitcnt lgkmcnt(0)
	s_nop 1
	v_add_f32_dpp v10, v13, v13 quad_perm:[1,0,3,2] row_mask:0xf bank_mask:0xf
	v_mul_f32_e32 v9, v22, v8
	v_mul_f32_e32 v9, v51, v9
	v_bfe_u32 v21, v9, 16, 1
	v_add3_u32 v9, v9, v21, s76
	s_waitcnt lgkmcnt(0)
	s_nop 1
	v_add_f32_dpp v10, v10, v10 quad_perm:[2,3,0,1] row_mask:0xf bank_mask:0xf
	global_store_short_d16_hi v[6:7], v9, off offset:128
	v_mul_f32_e32 v9, v20, v8
	v_mul_f32_e32 v9, v50, v9
	v_bfe_u32 v20, v9, 16, 1
	v_add3_u32 v9, v9, v20, s76
	global_store_short_d16_hi v[6:7], v9, off offset:160
	s_waitcnt lgkmcnt(0)
	s_nop 1
	v_add_f32_dpp v9, v10, v10 row_half_mirror row_mask:0xf bank_mask:0xf
	v_mul_f32_e32 v13, v26, v8
	v_mul_f32_e32 v13, v49, v13
	v_bfe_u32 v20, v13, 16, 1
	v_add3_u32 v13, v13, v20, s76
	s_waitcnt lgkmcnt(0)
	s_nop 1
	v_add_f32_dpp v9, v9, v9 row_mirror row_mask:0xf bank_mask:0xf
	v_fmamk_f32 v9, v9, 0x3c000000, v205
	v_mul_f32_e32 v10, 0x4f800000, v9
	v_cmp_gt_f32_e32 vcc, s75, v9
	global_store_short_d16_hi v[6:7], v13, off offset:192
	v_mul_f32_e32 v8, v24, v8
	v_cndmask_b32_e32 v9, v9, v10, vcc
	v_sqrt_f32_e32 v10, v9
	v_mul_f32_e32 v8, v0, v8
	v_or_b32_e32 v4, 19, v4
	v_lshlrev_b64 v[4:5], 11, v[4:5]
	v_add_u32_e32 v13, -1, v10
	v_fma_f32 v20, -v13, v10, v9
	v_cmp_ge_f32_e64 s[0:1], 0, v20
	v_add_u32_e32 v20, 1, v10
	v_lshl_add_u64 v[2:3], v[2:3], 0, v[4:5]
	v_cndmask_b32_e64 v13, v10, v13, s[0:1]
	v_fma_f32 v10, -v20, v10, v9
	v_cmp_lt_f32_e64 s[0:1], 0, v10
	s_nop 1
	v_cndmask_b32_e64 v10, v13, v20, s[0:1]
	v_mul_f32_e32 v13, 0x37800000, v10
	v_cndmask_b32_e32 v10, v10, v13, vcc
	v_cmp_class_f32_e32 vcc, v9, v206
	v_bfe_u32 v20, v8, 16, 1
	v_add3_u32 v8, v8, v20, s76
	v_cndmask_b32_e32 v9, v10, v9, vcc
	v_div_scale_f32 v10, s[0:1], v9, v9, 1.0
	v_rcp_f32_e32 v13, v10
	global_store_short_d16_hi v[6:7], v8, off offset:224
	v_fma_f32 v6, -v10, v13, 1.0
	v_fmac_f32_e32 v13, v6, v13
	v_div_scale_f32 v6, vcc, 1.0, v9, 1.0
	v_mul_f32_e32 v7, v6, v13
	v_fma_f32 v8, -v10, v7, v6
	v_fmac_f32_e32 v7, v8, v13
	v_fma_f32 v6, -v10, v7, v6
	v_div_fmas_f32 v6, v6, v13, v7
	v_div_fixup_f32 v6, v6, v9, 1.0
	v_mul_f32_e32 v4, v11, v6
	v_mul_f32_e32 v4, v62, v4
	v_bfe_u32 v5, v4, 16, 1
	v_add3_u32 v4, v4, v5, s76
	global_store_short_d16_hi v[2:3], v4, off
	v_mul_f32_e32 v4, v12, v6
	v_mul_f32_e32 v4, v55, v4
	v_bfe_u32 v5, v4, 16, 1
	v_add3_u32 v4, v4, v5, s76
	global_store_short_d16_hi v[2:3], v4, off offset:32
	v_mul_f32_e32 v4, v14, v6
	v_mul_f32_e32 v4, v54, v4
	v_bfe_u32 v5, v4, 16, 1
	v_add3_u32 v4, v4, v5, s76
	global_store_short_d16_hi v[2:3], v4, off offset:64
	v_mul_f32_e32 v4, v15, v6
	v_mul_f32_e32 v4, v53, v4
	v_bfe_u32 v5, v4, 16, 1
	v_add3_u32 v4, v4, v5, s76
	global_store_short_d16_hi v[2:3], v4, off offset:96
	v_mul_f32_e32 v4, v16, v6
	v_mul_f32_e32 v4, v51, v4
	v_bfe_u32 v5, v4, 16, 1
	v_add3_u32 v4, v4, v5, s76
	global_store_short_d16_hi v[2:3], v4, off offset:128
	v_mul_f32_e32 v4, v17, v6
	v_mul_f32_e32 v4, v50, v4
	v_bfe_u32 v5, v4, 16, 1
	v_add3_u32 v4, v4, v5, s76
	global_store_short_d16_hi v[2:3], v4, off offset:160
	v_mul_f32_e32 v4, v18, v6
	v_mul_f32_e32 v4, v49, v4
	v_bfe_u32 v5, v4, 16, 1
	v_add3_u32 v4, v4, v5, s76
	global_store_short_d16_hi v[2:3], v4, off offset:192
	v_mul_f32_e32 v4, v19, v6
	v_mul_f32_e32 v0, v0, v4
	v_bfe_u32 v4, v0, 16, 1
	v_add3_u32 v0, v0, v4, s76
	global_store_short_d16_hi v[2:3], v0, off offset:224
